# pool rewrite + GEMM K-loops: s_setprio flips deleted, one static s_setprio 1 for waves 0-3 (other half than previous version)
# speedup vs baseline: 1.0243x; 1.0070x over previous
; template <class Epi>
; __device__ __forceinline__ void gemm_phase(LAS unsigned char* lds, const Gemm g, const StaticOrder& S, const Epi& E) {
;     ...
;         const bool has_next = S.next(ui + 1, nxt);
;         const char* nA = has_next ? (const char*)g.A + (size_t)nxt.pm * tstepA + (size_t)(nxt.pn >> 2) * gstepA : cA; const char* nB = has_next ? (const char*)g.Bt + (size_t)nxt.pn * tstepB : cB;
;         for (int t = 0; t < nt; t += 2) {
;             const bool last = (t == nt - 2);
;             const char* a1 = cA + (size_t)(t + 1) * kstepA;
;             const char* a2 = last ? nA : cA + (size_t)(t + 2) * kstepA; const char* b2 = last ? nB : cB + (size_t)(t + 2) * kstep;
;     ...
;         for (int a = 0; a < 2; ++a)
; #pragma unroll
;             for (int b = 0; b < 2; ++b)
; #pragma unroll
;                 for (int m = 0; m < 4; ++m)
; #pragma unroll
;                     for (int n = 0; n < 2; ++n) acc[a][b][m][n] = (f32x4){0.f, 0.f, 0.f, 0.f};
.LBB0_157:
	s_ashr_i32 s23, s22, 31
	s_lshl_b64 s[24:25], s[22:23], 20
	s_add_u32 s26, s10, s24
	s_addc_u32 s27, s11, s25
	s_and_b64 s[24:25], s[40:41], exec
	s_cselect_b32 s23, s27, s39
	s_cselect_b32 s55, s26, s38
	s_ashr_i32 s21, s20, 31
	s_lshl_b64 s[24:25], s[20:21], 20
	s_add_u32 s36, s35, s24
	s_addc_u32 s37, s44, s25
	s_and_b64 s[24:25], s[40:41], exec
	s_cselect_b32 s21, s37, s5
	s_cselect_b32 s56, s36, s4
	s_add_u32 s57, s4, 0x100
	v_mov_b32_e32 v2, 0
	s_addc_u32 s58, s5, 0
	s_mov_b32 s59, -2
	v_mov_b32_e32 v3, v2
	v_mov_b32_e32 v4, v2
	v_mov_b32_e32 v5, v2
	v_mov_b32_e32 v6, v2
	v_mov_b32_e32 v7, v2
	v_mov_b32_e32 v8, v2
	v_mov_b32_e32 v9, v2
	v_mov_b32_e32 v18, v2
	v_mov_b32_e32 v19, v2
	v_mov_b32_e32 v20, v2
	v_mov_b32_e32 v21, v2
	v_mov_b32_e32 v22, v2
	v_mov_b32_e32 v23, v2
	v_mov_b32_e32 v24, v2
	v_mov_b32_e32 v25, v2
	v_mov_b32_e32 v34, v2
	v_mov_b32_e32 v35, v2
	v_mov_b32_e32 v36, v2
	v_mov_b32_e32 v37, v2
	v_mov_b32_e32 v38, v2
	v_mov_b32_e32 v39, v2
	v_mov_b32_e32 v40, v2
	v_mov_b32_e32 v41, v2
	v_mov_b32_e32 v50, v2
	v_mov_b32_e32 v51, v2
	v_mov_b32_e32 v52, v2
	v_mov_b32_e32 v53, v2
	v_mov_b32_e32 v54, v2
	v_mov_b32_e32 v55, v2
	v_mov_b32_e32 v56, v2
	v_mov_b32_e32 v57, v2
	v_mov_b32_e32 v10, v2
	v_mov_b32_e32 v11, v2
	v_mov_b32_e32 v12, v2
	v_mov_b32_e32 v13, v2
	v_mov_b32_e32 v14, v2
	v_mov_b32_e32 v15, v2
	v_mov_b32_e32 v16, v2
	v_mov_b32_e32 v17, v2
	s_waitcnt vmcnt(0)
	v_mov_b32_e32 v26, v2
	v_mov_b32_e32 v27, v2
	v_mov_b32_e32 v28, v2
	v_mov_b32_e32 v29, v2
	v_mov_b32_e32 v30, v2
	v_mov_b32_e32 v31, v2
	v_mov_b32_e32 v32, v2
	v_mov_b32_e32 v33, v2
	v_mov_b32_e32 v42, v2
	v_mov_b32_e32 v43, v2
	v_mov_b32_e32 v44, v2
	v_mov_b32_e32 v45, v2
	v_mov_b32_e32 v46, v2
	v_mov_b32_e32 v47, v2
	v_mov_b32_e32 v48, v2
	v_mov_b32_e32 v49, v2
	v_mov_b32_e32 v58, v2
	v_mov_b32_e32 v59, v2
	v_mov_b32_e32 v60, v2
	v_mov_b32_e32 v61, v2
	v_mov_b32_e32 v62, v2
	v_mov_b32_e32 v63, v2
	v_mov_b32_e32 v64, v2
	v_mov_b32_e32 v65, v2
	v_mov_b32_e32 v66, v2
	v_mov_b32_e32 v67, v2
	v_mov_b32_e32 v68, v2
	v_mov_b32_e32 v69, v2
	v_mov_b32_e32 v70, v2
	v_mov_b32_e32 v71, v2
	v_mov_b32_e32 v72, v2
	v_mov_b32_e32 v73, v2
	v_mov_b32_e32 v82, v2
	v_mov_b32_e32 v83, v2
	v_mov_b32_e32 v84, v2
	v_mov_b32_e32 v85, v2
	v_mov_b32_e32 v86, v2
	v_mov_b32_e32 v87, v2
	v_mov_b32_e32 v88, v2
	v_mov_b32_e32 v89, v2
	v_mov_b32_e32 v98, v2
	v_mov_b32_e32 v99, v2
	v_mov_b32_e32 v100, v2
	v_mov_b32_e32 v101, v2
	v_mov_b32_e32 v102, v2
	v_mov_b32_e32 v103, v2
	v_mov_b32_e32 v104, v2
	v_mov_b32_e32 v105, v2
	v_mov_b32_e32 v114, v2
	v_mov_b32_e32 v115, v2
	v_mov_b32_e32 v116, v2
	v_mov_b32_e32 v117, v2
	v_mov_b32_e32 v118, v2
	v_mov_b32_e32 v119, v2
	v_mov_b32_e32 v120, v2
	v_mov_b32_e32 v121, v2
	v_mov_b32_e32 v74, v2
	v_mov_b32_e32 v75, v2
	v_mov_b32_e32 v76, v2
	v_mov_b32_e32 v77, v2
	v_mov_b32_e32 v78, v2
	v_mov_b32_e32 v79, v2
	v_mov_b32_e32 v80, v2
	v_mov_b32_e32 v81, v2
	v_mov_b32_e32 v90, v2
	v_mov_b32_e32 v91, v2
	v_mov_b32_e32 v92, v2
	v_mov_b32_e32 v93, v2
	v_mov_b32_e32 v94, v2
	v_mov_b32_e32 v95, v2
	v_mov_b32_e32 v96, v2
	v_mov_b32_e32 v97, v2
	v_mov_b32_e32 v106, v2
	v_mov_b32_e32 v107, v2
	v_mov_b32_e32 v108, v2
	v_mov_b32_e32 v109, v2
	v_mov_b32_e32 v110, v2
	v_mov_b32_e32 v111, v2
	v_mov_b32_e32 v112, v2
	v_mov_b32_e32 v113, v2
	v_mov_b32_e32 v122, v2
	v_mov_b32_e32 v123, v2
	v_mov_b32_e32 v124, v2
	v_mov_b32_e32 v125, v2
	v_mov_b32_e32 v126, v2
	v_mov_b32_e32 v127, v2
	v_mov_b32_e32 v128, v2
	v_mov_b32_e32 v129, v2
	v_readfirstlane_b32 s100, v232
	s_nop 3
	s_cmp_ge_u32 s100, 0x100
	s_cbranch_scc1 .Lprio_skip_0
	s_setprio 1

; template <class Epi>
; __device__ __forceinline__ void gemm_phase(LAS unsigned char* lds, const Gemm g, const StaticOrder& S, const Epi& E) {
;     ...
;         const bool has_next = S.next(ui + 1, nxt);
;         const char* nA = has_next ? (const char*)g.A + (size_t)nxt.pm * tstepA + (size_t)(nxt.pn >> 2) * gstepA : cA; const char* nB = has_next ? (const char*)g.Bt + (size_t)nxt.pn * tstepB : cB;
;         for (int t = 0; t < nt; t += 2) {
;             const bool last = (t == nt - 2);
;             const char* a1 = cA + (size_t)(t + 1) * kstepA;
;             const char* a2 = last ? nA : cA + (size_t)(t + 2) * kstepA; const char* b2 = last ? nB : cB + (size_t)(t + 2) * kstep;
;     ...
;         for (int a = 0; a < 2; ++a)
; #pragma unroll
;             for (int b = 0; b < 2; ++b)
; #pragma unroll
;                 for (int m = 0; m < 4; ++m)
; #pragma unroll
;                     for (int n = 0; n < 2; ++n) acc[a][b][m][n] = (f32x4){0.f, 0.f, 0.f, 0.f};
.LBB0_358:
	v_mov_b64_e32 v[2:3], 0x100
	s_ashr_i32 s17, s16, 31
	v_cmp_lt_i64_e32 vcc, s[18:19], v[2:3]
	s_lshl_b64 s[18:19], s[16:17], 21
	s_add_u32 s18, s38, s18
	s_addc_u32 s19, s39, s19
	s_and_b64 s[20:21], vcc, exec
	s_cselect_b32 s17, s19, s23
	s_cselect_b32 s60, s18, s22
	s_ashr_i32 s15, s14, 31
	s_lshl_b64 s[20:21], s[14:15], 21
	s_add_u32 s20, s46, s20
	s_addc_u32 s21, s47, s21
	s_and_b64 s[24:25], vcc, exec
	s_cselect_b32 s15, s21, s27
	s_cselect_b32 s61, s20, s26
	s_add_u32 s62, s26, 0x100
	v_mov_b32_e32 v2, 0
	s_addc_u32 s63, s27, 0
	s_mov_b32 s64, -2
	v_mov_b32_e32 v3, v2
	v_mov_b32_e32 v4, v2
	v_mov_b32_e32 v5, v2
	v_mov_b32_e32 v6, v2
	v_mov_b32_e32 v7, v2
	v_mov_b32_e32 v8, v2
	v_mov_b32_e32 v9, v2
	v_mov_b32_e32 v18, v2
	v_mov_b32_e32 v19, v2
	v_mov_b32_e32 v20, v2
	v_mov_b32_e32 v21, v2
	v_mov_b32_e32 v22, v2
	v_mov_b32_e32 v23, v2
	v_mov_b32_e32 v24, v2
	v_mov_b32_e32 v25, v2
	v_mov_b32_e32 v34, v2
	v_mov_b32_e32 v35, v2
	v_mov_b32_e32 v36, v2
	v_mov_b32_e32 v37, v2
	v_mov_b32_e32 v38, v2
	v_mov_b32_e32 v39, v2
	v_mov_b32_e32 v40, v2
	v_mov_b32_e32 v41, v2
	v_mov_b32_e32 v50, v2
	v_mov_b32_e32 v51, v2
	v_mov_b32_e32 v52, v2
	v_mov_b32_e32 v53, v2
	v_mov_b32_e32 v54, v2
	v_mov_b32_e32 v55, v2
	v_mov_b32_e32 v56, v2
	v_mov_b32_e32 v57, v2
	v_mov_b32_e32 v10, v2
	v_mov_b32_e32 v11, v2
	v_mov_b32_e32 v12, v2
	v_mov_b32_e32 v13, v2
	v_mov_b32_e32 v14, v2
	v_mov_b32_e32 v15, v2
	v_mov_b32_e32 v16, v2
	v_mov_b32_e32 v17, v2
	v_mov_b32_e32 v26, v2
	v_mov_b32_e32 v27, v2
	v_mov_b32_e32 v28, v2
	v_mov_b32_e32 v29, v2
	v_mov_b32_e32 v30, v2
	v_mov_b32_e32 v31, v2
	v_mov_b32_e32 v32, v2
	v_mov_b32_e32 v33, v2
	v_mov_b32_e32 v42, v2
	v_mov_b32_e32 v43, v2
	v_mov_b32_e32 v44, v2
	v_mov_b32_e32 v45, v2
	v_mov_b32_e32 v46, v2
	v_mov_b32_e32 v47, v2
	v_mov_b32_e32 v48, v2
	v_mov_b32_e32 v49, v2
	v_mov_b32_e32 v58, v2
	v_mov_b32_e32 v59, v2
	v_mov_b32_e32 v60, v2
	v_mov_b32_e32 v61, v2
	v_mov_b32_e32 v62, v2
	v_mov_b32_e32 v63, v2
	v_mov_b32_e32 v64, v2
	v_mov_b32_e32 v65, v2
	v_mov_b32_e32 v66, v2
	v_mov_b32_e32 v67, v2
	v_mov_b32_e32 v68, v2
	v_mov_b32_e32 v69, v2
	v_mov_b32_e32 v78, v2
	v_mov_b32_e32 v79, v2
	v_mov_b32_e32 v80, v2
	v_mov_b32_e32 v81, v2
	v_mov_b32_e32 v98, v2
	v_mov_b32_e32 v99, v2
	v_mov_b32_e32 v100, v2
	v_mov_b32_e32 v101, v2
	v_mov_b32_e32 v102, v2
	v_mov_b32_e32 v103, v2
	v_mov_b32_e32 v104, v2
	v_mov_b32_e32 v105, v2
	v_mov_b32_e32 v114, v2
	v_mov_b32_e32 v115, v2
	v_mov_b32_e32 v116, v2
	v_mov_b32_e32 v117, v2
	v_mov_b32_e32 v118, v2
	v_mov_b32_e32 v119, v2
	v_mov_b32_e32 v120, v2
	v_mov_b32_e32 v121, v2
	v_mov_b32_e32 v130, v2
	v_mov_b32_e32 v131, v2
	v_mov_b32_e32 v132, v2
	v_mov_b32_e32 v133, v2
	v_mov_b32_e32 v134, v2
	v_mov_b32_e32 v135, v2
	v_mov_b32_e32 v136, v2
	v_mov_b32_e32 v137, v2
	v_mov_b32_e32 v90, v2
	v_mov_b32_e32 v91, v2
	v_mov_b32_e32 v92, v2
	v_mov_b32_e32 v93, v2
	v_mov_b32_e32 v94, v2
	v_mov_b32_e32 v95, v2
	v_mov_b32_e32 v96, v2
	v_mov_b32_e32 v97, v2
	v_mov_b32_e32 v106, v2
	v_mov_b32_e32 v107, v2
	v_mov_b32_e32 v108, v2
	v_mov_b32_e32 v109, v2
	v_mov_b32_e32 v110, v2
	v_mov_b32_e32 v111, v2
	v_mov_b32_e32 v112, v2
	v_mov_b32_e32 v113, v2
	v_mov_b32_e32 v122, v2
	v_mov_b32_e32 v123, v2
	v_mov_b32_e32 v124, v2
	v_mov_b32_e32 v125, v2
	v_mov_b32_e32 v126, v2
	v_mov_b32_e32 v127, v2
	v_mov_b32_e32 v128, v2
	v_mov_b32_e32 v129, v2
	v_mov_b32_e32 v138, v2
	v_mov_b32_e32 v139, v2
	v_mov_b32_e32 v140, v2
	v_mov_b32_e32 v141, v2
	v_mov_b32_e32 v142, v2
	v_mov_b32_e32 v143, v2
	v_mov_b32_e32 v144, v2
	v_mov_b32_e32 v145, v2
	v_readfirstlane_b32 s100, v232
	s_nop 3
	s_cmp_ge_u32 s100, 0x100
	s_cbranch_scc1 .Lprio_skip_1
	s_setprio 1

; template <class Epi>
; __device__ __forceinline__ void gemm_phase(LAS unsigned char* lds, const Gemm g, const StaticOrder& S, const Epi& E) {
;     ...
;         const bool has_next = S.next(ui + 1, nxt);
;         const char* nA = has_next ? (const char*)g.A + (size_t)nxt.pm * tstepA + (size_t)(nxt.pn >> 2) * gstepA : cA; const char* nB = has_next ? (const char*)g.Bt + (size_t)nxt.pn * tstepB : cB;
;         for (int t = 0; t < nt; t += 2) {
;             const bool last = (t == nt - 2);
;             const char* a1 = cA + (size_t)(t + 1) * kstepA;
;             const char* a2 = last ? nA : cA + (size_t)(t + 2) * kstepA; const char* b2 = last ? nB : cB + (size_t)(t + 2) * kstep;
;             const char* a3 = a2 + kstepA; const char* b3 = b2 + kstep;
.LBB0_471:
	s_add_u32 s17, s20, 0x100
	s_addc_u32 s58, s21, 0
	s_ashr_i32 s11, s10, 31
	s_lshl_b64 s[14:15], s[10:11], 21
	s_add_u32 s18, s35, s14
	s_addc_u32 s19, s36, s15
	s_and_b64 s[14:15], s[42:43], exec
	s_cselect_b32 s11, s19, s5
	s_cselect_b32 s59, s18, s4
	s_ashr_i32 s9, s8, 31
	s_lshl_b64 s[14:15], s[8:9], 21
	s_add_u32 s14, s37, s14
	s_addc_u32 s15, s38, s15
	s_and_b64 s[22:23], s[42:43], exec
	s_cselect_b32 s9, s15, s21
	s_cselect_b32 s60, s14, s20
	s_add_u32 s20, s4, 0x100080
	s_addc_u32 s21, s5, 0
	v_lshl_add_u64 v[140:141], s[20:21], 0, v[136:137]
	v_lshl_add_u64 v[142:143], s[20:21], 0, v[138:139]
	s_mov_b32 s61, -2
	s_mov_b64 s[20:21], 0
	v_readfirstlane_b32 s100, v232
	s_nop 3
	s_cmp_ge_u32 s100, 0x100
	s_cbranch_scc1 .Lprio_skip_2
	s_setprio 1

; template <class Epi>
; __device__ __forceinline__ void gemm_phase(LAS unsigned char* lds, const Gemm g, const StaticOrder& S, const Epi& E) {
;     ...
;         const bool has_next = S.next(ui + 1, nxt);
;         const char* nA = has_next ? (const char*)g.A + (size_t)nxt.pm * tstepA + (size_t)(nxt.pn >> 2) * gstepA : cA; const char* nB = has_next ? (const char*)g.Bt + (size_t)nxt.pn * tstepB : cB;
;         for (int t = 0; t < nt; t += 2) {
;             const bool last = (t == nt - 2);
;             const char* a1 = cA + (size_t)(t + 1) * kstepA;
;             const char* a2 = last ? nA : cA + (size_t)(t + 2) * kstepA; const char* b2 = last ? nB : cB + (size_t)(t + 2) * kstep;
;     ...
;         for (int a = 0; a < 2; ++a)
; #pragma unroll
;             for (int b = 0; b < 2; ++b)
; #pragma unroll
;                 for (int m = 0; m < 4; ++m)
; #pragma unroll
;                     for (int n = 0; n < 2; ++n) acc[a][b][m][n] = (f32x4){0.f, 0.f, 0.f, 0.f};
.LBB0_602:
	s_ashr_i32 s53, s52, 31
	v_cmp_lt_i64_e32 vcc, s[4:5], v[182:183]
	s_lshl_b64 s[4:5], s[52:53], 21
	s_add_u32 s10, s15, s4
	s_addc_u32 s11, s16, s5
	s_ashr_i32 s4, s50, 2
	s_ashr_i32 s5, s4, 31
	s_lshl_b64 s[4:5], s[4:5], 11
	s_add_u32 s54, s10, s4
	s_addc_u32 s55, s11, s5
	s_and_b64 s[4:5], vcc, exec
	s_cselect_b32 s35, s55, s1
	s_cselect_b32 s36, s54, s0
	s_ashr_i32 s51, s50, 31
	s_lshl_b64 s[4:5], s[50:51], 19
	s_add_u32 s56, s17, s4
	s_addc_u32 s57, s18, s5
	s_and_b64 s[4:5], vcc, exec
	s_cselect_b32 s37, s57, s9
	s_cselect_b32 s51, s56, s8
	s_add_u32 s53, s8, 0x100
	v_mov_b32_e32 v2, 0
	s_addc_u32 s58, s9, 0
	s_mov_b32 s59, -2
	v_mov_b32_e32 v3, v2
	v_mov_b32_e32 v4, v2
	v_mov_b32_e32 v5, v2
	v_mov_b32_e32 v6, v2
	v_mov_b32_e32 v7, v2
	v_mov_b32_e32 v8, v2
	v_mov_b32_e32 v9, v2
	v_mov_b32_e32 v10, v2
	v_mov_b32_e32 v11, v2
	v_mov_b32_e32 v12, v2
	v_mov_b32_e32 v13, v2
	v_mov_b32_e32 v14, v2
	v_mov_b32_e32 v15, v2
	v_mov_b32_e32 v16, v2
	v_mov_b32_e32 v17, v2
	v_mov_b32_e32 v18, v2
	v_mov_b32_e32 v19, v2
	v_mov_b32_e32 v20, v2
	v_mov_b32_e32 v21, v2
	v_mov_b32_e32 v22, v2
	v_mov_b32_e32 v23, v2
	v_mov_b32_e32 v24, v2
	v_mov_b32_e32 v25, v2
	v_mov_b32_e32 v26, v2
	v_mov_b32_e32 v27, v2
	v_mov_b32_e32 v28, v2
	v_mov_b32_e32 v29, v2
	v_mov_b32_e32 v30, v2
	v_mov_b32_e32 v31, v2
	v_mov_b32_e32 v32, v2
	v_mov_b32_e32 v33, v2
	v_mov_b32_e32 v74, v2
	v_mov_b32_e32 v75, v2
	v_mov_b32_e32 v76, v2
	v_mov_b32_e32 v77, v2
	v_mov_b32_e32 v78, v2
	v_mov_b32_e32 v79, v2
	v_mov_b32_e32 v80, v2
	v_mov_b32_e32 v81, v2
	v_mov_b32_e32 v82, v2
	v_mov_b32_e32 v83, v2
	v_mov_b32_e32 v84, v2
	v_mov_b32_e32 v85, v2
	v_mov_b32_e32 v86, v2
	v_mov_b32_e32 v87, v2
	v_mov_b32_e32 v88, v2
	v_mov_b32_e32 v89, v2
	v_mov_b32_e32 v90, v2
	v_mov_b32_e32 v91, v2
	v_mov_b32_e32 v92, v2
	v_mov_b32_e32 v93, v2
	v_mov_b32_e32 v94, v2
	v_mov_b32_e32 v95, v2
	v_mov_b32_e32 v96, v2
	v_mov_b32_e32 v97, v2
	v_mov_b32_e32 v110, v2
	v_mov_b32_e32 v111, v2
	v_mov_b32_e32 v112, v2
	v_mov_b32_e32 v113, v2
	v_mov_b32_e32 v114, v2
	v_mov_b32_e32 v115, v2
	v_mov_b32_e32 v116, v2
	v_mov_b32_e32 v117, v2
	v_mov_b32_e32 v42, v2
	v_mov_b32_e32 v43, v2
	v_mov_b32_e32 v44, v2
	v_mov_b32_e32 v45, v2
	v_mov_b32_e32 v46, v2
	v_mov_b32_e32 v47, v2
	v_mov_b32_e32 v48, v2
	v_mov_b32_e32 v49, v2
	v_mov_b32_e32 v50, v2
	v_mov_b32_e32 v51, v2
	v_mov_b32_e32 v52, v2
	v_mov_b32_e32 v53, v2
	v_mov_b32_e32 v54, v2
	v_mov_b32_e32 v55, v2
	v_mov_b32_e32 v56, v2
	v_mov_b32_e32 v57, v2
	v_mov_b32_e32 v58, v2
	v_mov_b32_e32 v59, v2
	v_mov_b32_e32 v60, v2
	v_mov_b32_e32 v61, v2
	v_mov_b32_e32 v62, v2
	v_mov_b32_e32 v63, v2
	v_mov_b32_e32 v64, v2
	v_mov_b32_e32 v65, v2
	v_mov_b32_e32 v66, v2
	v_mov_b32_e32 v67, v2
	v_mov_b32_e32 v68, v2
	v_mov_b32_e32 v69, v2
	v_mov_b32_e32 v70, v2
	v_mov_b32_e32 v71, v2
	v_mov_b32_e32 v72, v2
	v_mov_b32_e32 v73, v2
	v_mov_b32_e32 v122, v2
	v_mov_b32_e32 v123, v2
	v_mov_b32_e32 v124, v2
	v_mov_b32_e32 v125, v2
	v_mov_b32_e32 v126, v2
	v_mov_b32_e32 v127, v2
	v_mov_b32_e32 v128, v2
	v_mov_b32_e32 v129, v2
	v_mov_b32_e32 v134, v2
	v_mov_b32_e32 v135, v2
	v_mov_b32_e32 v136, v2
	v_mov_b32_e32 v137, v2
	v_mov_b32_e32 v138, v2
	v_mov_b32_e32 v139, v2
	v_mov_b32_e32 v140, v2
	v_mov_b32_e32 v141, v2
	v_mov_b32_e32 v146, v2
	v_mov_b32_e32 v147, v2
	v_mov_b32_e32 v148, v2
	v_mov_b32_e32 v149, v2
	v_mov_b32_e32 v150, v2
	v_mov_b32_e32 v151, v2
	v_mov_b32_e32 v152, v2
	v_mov_b32_e32 v153, v2
	v_mov_b32_e32 v162, v2
	v_mov_b32_e32 v163, v2
	v_mov_b32_e32 v164, v2
	v_mov_b32_e32 v165, v2
	v_mov_b32_e32 v166, v2
	v_mov_b32_e32 v167, v2
	v_mov_b32_e32 v168, v2
	v_mov_b32_e32 v169, v2
	v_readfirstlane_b32 s100, v232
	s_nop 3
	s_cmp_ge_u32 s100, 0x100
	s_cbranch_scc1 .Lprio_skip_3
	s_setprio 1

; template <class Epi>
; __device__ __forceinline__ void gemm_phase(LAS unsigned char* lds, const Gemm g, const StaticOrder& S, const Epi& E) {
;     ...
;         const bool has_next = S.next(ui + 1, nxt);
;         const char* nA = has_next ? (const char*)g.A + (size_t)nxt.pm * tstepA + (size_t)(nxt.pn >> 2) * gstepA : cA; const char* nB = has_next ? (const char*)g.Bt + (size_t)nxt.pn * tstepB : cB;
;         for (int t = 0; t < nt; t += 2) {
;             const bool last = (t == nt - 2);
;             const char* a1 = cA + (size_t)(t + 1) * kstepA;
;             const char* a2 = last ? nA : cA + (size_t)(t + 2) * kstepA; const char* b2 = last ? nB : cB + (size_t)(t + 2) * kstep;
;     ...
;         for (int a = 0; a < 2; ++a)
; #pragma unroll
;             for (int b = 0; b < 2; ++b)
; #pragma unroll
;                 for (int m = 0; m < 4; ++m)
; #pragma unroll
;                     for (int n = 0; n < 2; ++n) acc[a][b][m][n] = (f32x4){0.f, 0.f, 0.f, 0.f};
.LBB0_795:
	s_ashr_i32 s51, s50, 31
	v_cmp_lt_i64_e32 vcc, s[4:5], v[182:183]
	s_lshl_b64 s[4:5], s[50:51], 13
	s_add_u32 s52, s42, s4
	s_addc_u32 s53, s43, s5
	s_and_b64 s[4:5], vcc, exec
	s_cselect_b32 s37, s53, s15
	s_cselect_b32 s38, s52, s14
	s_ashr_i32 s49, s48, 31
	s_lshl_b64 s[4:5], s[48:49], 21
	s_add_u32 s54, s19, s4
	s_addc_u32 s55, s20, s5
	s_and_b64 s[4:5], vcc, exec
	s_cselect_b32 s39, s55, s9
	s_cselect_b32 s49, s54, s8
	s_add_u32 s51, s8, 0x100
	s_addc_u32 s56, s9, 0
	s_add_u32 s8, s14, 0x105400
	v_mov_b32_e32 v2, 0
	s_addc_u32 s9, s15, 0
	s_mov_b32 s57, -2
	v_mov_b32_e32 v3, v2
	v_mov_b32_e32 v4, v2
	v_mov_b32_e32 v5, v2
	v_mov_b32_e32 v6, v2
	v_mov_b32_e32 v7, v2
	v_mov_b32_e32 v8, v2
	v_mov_b32_e32 v9, v2
	v_mov_b32_e32 v10, v2
	v_mov_b32_e32 v11, v2
	v_mov_b32_e32 v12, v2
	v_mov_b32_e32 v13, v2
	v_mov_b32_e32 v14, v2
	v_mov_b32_e32 v15, v2
	v_mov_b32_e32 v16, v2
	v_mov_b32_e32 v17, v2
	v_mov_b32_e32 v18, v2
	v_mov_b32_e32 v19, v2
	v_mov_b32_e32 v20, v2
	v_mov_b32_e32 v21, v2
	v_mov_b32_e32 v22, v2
	v_mov_b32_e32 v23, v2
	v_mov_b32_e32 v24, v2
	v_mov_b32_e32 v25, v2
	v_mov_b32_e32 v34, v2
	v_mov_b32_e32 v35, v2
	v_mov_b32_e32 v36, v2
	v_mov_b32_e32 v37, v2
	v_mov_b32_e32 v38, v2
	v_mov_b32_e32 v39, v2
	v_mov_b32_e32 v40, v2
	v_mov_b32_e32 v41, v2
	v_mov_b32_e32 v74, v2
	v_mov_b32_e32 v75, v2
	v_mov_b32_e32 v76, v2
	v_mov_b32_e32 v77, v2
	v_mov_b32_e32 v78, v2
	v_mov_b32_e32 v79, v2
	v_mov_b32_e32 v80, v2
	v_mov_b32_e32 v81, v2
	v_mov_b32_e32 v82, v2
	v_mov_b32_e32 v83, v2
	v_mov_b32_e32 v84, v2
	v_mov_b32_e32 v85, v2
	v_mov_b32_e32 v86, v2
	v_mov_b32_e32 v87, v2
	v_mov_b32_e32 v88, v2
	v_mov_b32_e32 v89, v2
	v_mov_b32_e32 v90, v2
	v_mov_b32_e32 v91, v2
	v_mov_b32_e32 v92, v2
	v_mov_b32_e32 v93, v2
	v_mov_b32_e32 v94, v2
	v_mov_b32_e32 v95, v2
	v_mov_b32_e32 v96, v2
	v_mov_b32_e32 v97, v2
	v_mov_b32_e32 v106, v2
	v_mov_b32_e32 v107, v2
	v_mov_b32_e32 v108, v2
	v_mov_b32_e32 v109, v2
	v_mov_b32_e32 v110, v2
	v_mov_b32_e32 v111, v2
	v_mov_b32_e32 v112, v2
	v_mov_b32_e32 v113, v2
	v_mov_b32_e32 v42, v2
	v_mov_b32_e32 v43, v2
	v_mov_b32_e32 v44, v2
	v_mov_b32_e32 v45, v2
	v_mov_b32_e32 v46, v2
	v_mov_b32_e32 v47, v2
	v_mov_b32_e32 v48, v2
	v_mov_b32_e32 v49, v2
	v_mov_b32_e32 v50, v2
	v_mov_b32_e32 v51, v2
	v_mov_b32_e32 v52, v2
	v_mov_b32_e32 v53, v2
	v_mov_b32_e32 v54, v2
	v_mov_b32_e32 v55, v2
	v_mov_b32_e32 v56, v2
	v_mov_b32_e32 v57, v2
	v_mov_b32_e32 v58, v2
	v_mov_b32_e32 v59, v2
	v_mov_b32_e32 v60, v2
	v_mov_b32_e32 v61, v2
	v_mov_b32_e32 v62, v2
	v_mov_b32_e32 v63, v2
	v_mov_b32_e32 v64, v2
	v_mov_b32_e32 v65, v2
	v_mov_b32_e32 v66, v2
	v_mov_b32_e32 v67, v2
	v_mov_b32_e32 v68, v2
	v_mov_b32_e32 v69, v2
	v_mov_b32_e32 v70, v2
	v_mov_b32_e32 v71, v2
	v_mov_b32_e32 v72, v2
	v_mov_b32_e32 v73, v2
	v_mov_b32_e32 v114, v2
	v_mov_b32_e32 v115, v2
	v_mov_b32_e32 v116, v2
	v_mov_b32_e32 v117, v2
	v_mov_b32_e32 v118, v2
	v_mov_b32_e32 v119, v2
	v_mov_b32_e32 v120, v2
	v_mov_b32_e32 v121, v2
	v_mov_b32_e32 v122, v2
	v_mov_b32_e32 v123, v2
	v_mov_b32_e32 v124, v2
	v_mov_b32_e32 v125, v2
	v_mov_b32_e32 v126, v2
	v_mov_b32_e32 v127, v2
	v_mov_b32_e32 v128, v2
	v_mov_b32_e32 v129, v2
	v_mov_b32_e32 v134, v2
	v_mov_b32_e32 v135, v2
	v_mov_b32_e32 v136, v2
	v_mov_b32_e32 v137, v2
	v_mov_b32_e32 v138, v2
	v_mov_b32_e32 v139, v2
	v_mov_b32_e32 v140, v2
	v_mov_b32_e32 v141, v2
	v_mov_b32_e32 v158, v2
	v_mov_b32_e32 v159, v2
	v_mov_b32_e32 v160, v2
	v_mov_b32_e32 v161, v2
	v_mov_b32_e32 v162, v2
	v_mov_b32_e32 v163, v2
	v_mov_b32_e32 v164, v2
	v_mov_b32_e32 v165, v2
	v_readfirstlane_b32 s100, v232
	s_nop 3
	s_cmp_ge_u32 s100, 0x100
	s_cbranch_scc1 .Lprio_skip_4
	s_setprio 1
